# natten per-step K-row RMS wave reduction via DPP row_ror + v_permlane16/32_swap instead of three serial ds_bpermute round trips
# baseline (speedup 1.0000x reference)
.LBB0_517:
	s_waitcnt vmcnt(3)
	v_and_b32_e32 v187, 0xffff0000, v3
	v_and_b32_e32 v186, 0xffff0000, v2
	v_and_b32_e32 v195, 0xffff0000, v5
	v_and_b32_e32 v194, 0xffff0000, v4
	s_waitcnt vmcnt(2)
	v_lshlrev_b32_e32 v181, 16, v6
	v_and_b32_e32 v206, 0xffff0000, v6
	v_lshlrev_b32_e32 v190, 16, v8
	v_lshlrev_b32_e32 v185, 16, v3
	v_lshlrev_b32_e32 v184, 16, v2
	v_pk_mul_f32 v[188:189], v[186:187], v[186:187]
	v_lshlrev_b32_e32 v193, 16, v5
	v_lshlrev_b32_e32 v192, 16, v4
	v_pk_mul_f32 v[196:197], v[194:195], v[194:195]
	v_lshlrev_b32_e32 v200, 16, v7
	v_pk_fma_f32 v[188:189], v[184:185], v[184:185], v[188:189]
	v_pk_fma_f32 v[196:197], v[192:193], v[192:193], v[196:197]
	v_mul_f32_e32 v191, v181, v181
	v_mul_f32_e32 v199, v206, v206
	v_and_b32_e32 v201, 0xffff0000, v7
	v_mul_f32_e32 v182, v200, v200
	v_mov_b32_e32 v198, v190
	v_and_b32_e32 v207, 0xffff0000, v8
	v_lshlrev_b32_e32 v208, 16, v9
	v_and_b32_e32 v209, 0xffff0000, v9
	v_pk_add_f32 v[188:189], v[188:189], v[188:189] op_sel_hi:[0,1]
	v_pk_add_f32 v[196:197], v[196:197], v[196:197] op_sel_hi:[0,1]
	v_pk_fma_f32 v[202:203], v[200:201], v[200:201], v[182:183] op_sel_hi:[1,1,0]
	v_pk_add_f32 v[198:199], v[190:191], v[198:199]
	v_mul_f32_e32 v202, v207, v207
	v_mul_f32_e32 v188, v208, v208
	v_mul_f32_e32 v196, v209, v209
	v_mul_f32_e32 v204, v190, v190
	v_mov_b32_e32 v205, v199
	v_pk_add_f32 v[198:199], v[204:205], v[202:203]
	v_pk_add_f32 v[188:189], v[188:189], v[196:197]
	s_add_i32 s52, s80, 0x8000
	v_pk_add_f32 v[188:189], v[198:199], v[188:189]
	s_and_b32 s36, s52, 0x8000
	v_add_f32_e32 v182, v188, v189
	s_nop 1
	s_add_i32 s36, s36, 0
	s_waitcnt lgkmcnt(0)
	v_add_f32_dpp v182, v182, v182 row_ror:8 row_mask:0xf bank_mask:0xf
	v_mov_b32_e32 v188, v182
	s_nop 1
	v_permlane16_swap_b32_e32 v182, v188
	v_add_f32_e32 v182, v182, v188
	v_mov_b32_e32 v188, v182
	s_nop 1
	v_permlane32_swap_b32_e32 v182, v188
	v_add_f32_e32 v182, v182, v188
	v_fmamk_f32 v182, v182, 0x3c000000, v179
	v_cmp_gt_f32_e32 vcc, s60, v182
	v_mul_f32_e32 v188, 0x4b800000, v182
	s_nop 0
	v_cndmask_b32_e32 v182, v182, v188, vcc
	v_rsq_f32_e32 v182, v182
	s_nop 0
	v_mul_f32_e32 v188, 0x45800000, v182
	v_cndmask_b32_e32 v182, v182, v188, vcc
	v_mul_f32_e32 v184, v182, v184
	v_mul_f32_e32 v186, v182, v186
	v_cvt_pk_bf16_f32 v184, v184, v186
	v_mul_f32_e32 v185, v182, v185
	v_mul_f32_e32 v186, v182, v187
	v_cvt_pk_bf16_f32 v185, v185, v186
	v_mul_f32_e32 v186, v182, v192
	v_mul_f32_e32 v187, v182, v194
	v_cvt_pk_bf16_f32 v186, v186, v187
	v_mul_f32_e32 v187, v182, v193
	v_mul_f32_e32 v188, v182, v195
	v_cvt_pk_bf16_f32 v187, v187, v188
	v_mul_f32_e32 v181, v182, v181
	v_mul_f32_e32 v188, v182, v206
	v_cvt_pk_bf16_f32 v188, v181, v188
	v_mul_f32_e32 v181, v182, v200
	v_mul_f32_e32 v189, v182, v201
	v_cvt_pk_bf16_f32 v189, v181, v189
	v_mul_f32_e32 v181, v182, v190
	v_mul_f32_e32 v190, v182, v207
	v_cvt_pk_bf16_f32 v190, v181, v190
	v_mul_f32_e32 v181, v182, v208
	v_mul_f32_e32 v182, v182, v209
	v_cvt_pk_bf16_f32 v191, v181, v182
	v_add_u32_e32 v181, s36, v115
	ds_write_b128 v181, v[184:187]
	ds_write_b128 v181, v[188:191] offset:8192
	v_add_u32_e32 v181, s36, v127
	s_waitcnt vmcnt(1)
	ds_write_b128 v181, v[10:13] offset:16384
	v_add_u32_e32 v181, s36, v129
	s_waitcnt vmcnt(0)
	ds_write_b128 v181, v[14:17] offset:16384
